# P7 on Y workgroups gated only by the W_glu conversion waves (per-wave write-through arrive), not by the whole conversion job
# speedup vs baseline: 1.0187x; 1.0108x over previous
; #define LAS __attribute__((address_space(3)))
; #define LDS_WAIT() asm volatile("s_waitcnt lgkmcnt(0)" ::: "memory")
; __device__ __forceinline__ unsigned pk2(float lo, float hi) { return f2bf(lo) | (f2bf(hi) << 16); }
; __device__ __forceinline__ void p0_transpose_item(const float* W, int K, int N, bf16* WT, const float* gain, int mode, LAS float* scr, int item, int lane) {
;     const int nblk = N / 64, kb = item / nblk, nb = item % nblk, k0 = 64 * kb, n00 = 64 * nb;
;     f32x4 w[2][8]; float gn[8];
; #pragma unroll
;     for (int hf = 0; hf < 2; ++hf)
; #pragma unroll
;         for (int i = 0; i < 8; ++i) w[hf][i] = __builtin_nontemporal_load((const f32x4*)(W + (size_t)(k0 + (lane >> 3) + 8 * i) * N + n00 + 32 * hf + 4 * (lane & 7)));
; #pragma unroll
;     for (int i = 0; i < 8; ++i) gn[i] = gain ? gain[k0 + (lane >> 3) + 8 * i] : 1.0f;
; #pragma unroll
;     for (int hf = 0; hf < 2; ++hf) { const int n0 = n00 + 32 * hf;
; #pragma unroll
;       for (int i = 0; i < 8; ++i) { const int kk = (lane >> 3) + 8 * i; LAS float* d = scr + kk * 33 + 4 * (lane & 7);
;           d[0] = w[hf][i].x * gn[i]; d[1] = w[hf][i].y * gn[i]; d[2] = w[hf][i].z * gn[i]; d[3] = w[hf][i].w * gn[i]; }
;     LDS_WAIT(); asm volatile("" ::: "memory");
;     const int c = lane & 7;
; #pragma unroll
;     for (int j = 0; j < 4; ++j) { const int n = (lane >> 3) + 8 * j; const LAS float* s = scr + (8 * c) * 33 + n;
;         v4u o; o.x = pk2(s[0 * 33], s[1 * 33]); o.y = pk2(s[2 * 33], s[3 * 33]); o.z = pk2(s[4 * 33], s[5 * 33]); o.w = pk2(s[6 * 33], s[7 * 33]);
;         const int ng = n0 + n; int row;
;         if (mode == 0) row = ng;
;         else if (mode == 3) {
;             if (ng < 512) row = (ng & ~255) + 128 * ((ng >> 5) & 1) + 32 * ((ng >> 6) & 3) + (ng & 31);
;             else if (ng < 640) row = 512 + 128 * ((ng >> 5) & 1) + 32 * ((ng >> 6) & 1) + (ng & 31);
;             else if (ng < 768) { const int vi = ng - 640; row = 512 + 128 * ((vi >> 5) & 1) + 32 * (2 + (vi >> 6)) + (vi & 31); }
;             else row = ng; }
;         else row = (ng >> 7) * 256 + (ng & 127) + (mode == 2 ? 128 : 0);
;         *(v4u*)(WT + (size_t)row * K + k0 + 8 * c) = o; }
;     LDS_WAIT(); asm volatile("" ::: "memory"); }
.LBB0_914:
	s_andn2_b64 vcc, exec, s[0:1]
	s_cbranch_vccnz .LBB0_835
	s_ashr_i32 s0, s4, 31
	s_lshr_b32 s0, s0, 29
	s_add_i32 s0, s4, s0
	s_ashr_i32 s0, s0, 3
	s_lshl_b32 s16, s0, 6
	s_lshl_b32 s0, s0, 9
	s_sub_i32 s0, s5, s0
	v_or_b32_e32 v2, s16, v1
	s_ashr_i32 s1, s0, 31
	v_ashrrev_i32_e32 v3, 31, v2
	v_lshl_add_u64 v[32:33], s[0:1], 2, v[98:99]
	v_lshlrev_b64 v[4:5], 11, v[2:3]
	v_or_b32_e32 v8, 8, v2
	v_lshl_add_u64 v[36:37], v[32:33], 0, v[4:5]
	v_ashrrev_i32_e32 v9, 31, v8
	global_load_dwordx4 v[4:7], v[36:37], off nt
	v_lshlrev_b64 v[8:9], 11, v[8:9]
	v_or_b32_e32 v12, 16, v2
	v_lshl_add_u64 v[40:41], v[32:33], 0, v[8:9]
	v_ashrrev_i32_e32 v13, 31, v12
	global_load_dwordx4 v[8:11], v[40:41], off nt
	v_lshlrev_b64 v[12:13], 11, v[12:13]
	v_or_b32_e32 v16, 24, v2
	v_lshl_add_u64 v[44:45], v[32:33], 0, v[12:13]
	v_ashrrev_i32_e32 v17, 31, v16
	global_load_dwordx4 v[12:15], v[44:45], off nt
	v_lshlrev_b64 v[16:17], 11, v[16:17]
	v_or_b32_e32 v20, 32, v2
	v_lshl_add_u64 v[48:49], v[32:33], 0, v[16:17]
	v_ashrrev_i32_e32 v21, 31, v20
	global_load_dwordx4 v[16:19], v[48:49], off nt
	v_lshlrev_b64 v[20:21], 11, v[20:21]
	v_or_b32_e32 v24, 40, v2
	v_lshl_add_u64 v[52:53], v[32:33], 0, v[20:21]
	v_ashrrev_i32_e32 v25, 31, v24
	global_load_dwordx4 v[20:23], v[52:53], off nt
	v_lshlrev_b64 v[24:25], 11, v[24:25]
	v_or_b32_e32 v28, 48, v2
	v_lshl_add_u64 v[56:57], v[32:33], 0, v[24:25]
	v_ashrrev_i32_e32 v29, 31, v28
	global_load_dwordx4 v[24:27], v[56:57], off nt
	v_lshlrev_b64 v[28:29], 11, v[28:29]
	v_or_b32_e32 v2, 56, v2
	v_lshl_add_u64 v[60:61], v[32:33], 0, v[28:29]
	v_ashrrev_i32_e32 v3, 31, v2
	global_load_dwordx4 v[28:31], v[60:61], off nt
	v_lshlrev_b64 v[2:3], 11, v[2:3]
	v_lshl_add_u64 v[64:65], v[32:33], 0, v[2:3]
	global_load_dwordx4 v[32:35], v[64:65], off nt
	s_nop 0
	global_load_dwordx4 v[36:39], v[36:37], off offset:128 nt
	s_nop 0
	global_load_dwordx4 v[40:43], v[40:41], off offset:128 nt
	s_nop 0
	global_load_dwordx4 v[44:47], v[44:45], off offset:128 nt
	s_nop 0
	global_load_dwordx4 v[48:51], v[48:49], off offset:128 nt
	s_nop 0
	global_load_dwordx4 v[52:55], v[52:53], off offset:128 nt
	s_nop 0
	global_load_dwordx4 v[56:59], v[56:57], off offset:128 nt
	s_nop 0
	global_load_dwordx4 v[60:63], v[60:61], off offset:128 nt
	s_nop 0
	global_load_dwordx4 v[126:129], v[64:65], off offset:128 nt
	v_add_u32_e32 v66, 0x18c8, v103
	v_add_u32_e32 v102, 0x1ce0, v103
	v_add_u32_e32 v104, 0x1ce8, v103
	s_ashr_i32 s17, s16, 31
	v_lshl_add_u64 v[2:3], s[16:17], 1, v[100:101]
	s_waitcnt vmcnt(15)
	ds_write2_b32 v103, v4, v5 offset1:1
	ds_write2_b32 v103, v6, v7 offset0:2 offset1:3
	s_waitcnt vmcnt(14)
	ds_write2_b32 v113, v8, v9 offset1:1
	ds_write2_b32 v113, v10, v11 offset0:2 offset1:3
	s_waitcnt vmcnt(13)
	ds_write2_b32 v115, v12, v13 offset1:1
	ds_write2_b32 v117, v14, v15 offset1:1
	s_waitcnt vmcnt(12)
	ds_write2_b32 v118, v16, v17 offset1:1
	ds_write2_b32 v119, v18, v19 offset1:1
	s_waitcnt vmcnt(11)
	ds_write2_b32 v120, v20, v21 offset1:1
	ds_write2_b32 v121, v22, v23 offset1:1
	s_waitcnt vmcnt(10)
	ds_write2_b32 v122, v24, v25 offset1:1
	ds_write2_b32 v124, v26, v27 offset1:1
	s_waitcnt vmcnt(9)
	ds_write2_b32 v125, v28, v29 offset1:1
	ds_write2_b32 v66, v30, v31 offset1:1
	s_waitcnt vmcnt(8)
	ds_write2_b32 v102, v32, v33 offset1:1
	ds_write2_b32 v104, v34, v35 offset1:1
	s_waitcnt lgkmcnt(0)
	ds_read2_b32 v[10:11], v111 offset0:33 offset1:41
	ds_read2_b32 v[12:13], v111 offset1:8
	ds_read2_b32 v[14:15], v111 offset0:66 offset1:74
	ds_read2_b32 v[16:17], v111 offset0:99 offset1:107
	ds_read2_b32 v[18:19], v111 offset0:132 offset1:140
	ds_read2_b32 v[20:21], v111 offset0:165 offset1:173
	ds_read2_b32 v[22:23], v111 offset0:198 offset1:206
	s_waitcnt lgkmcnt(5)
	v_bfe_u32 v4, v12, 16, 1
	v_bfe_u32 v5, v10, 16, 1
	s_waitcnt lgkmcnt(4)
	v_bfe_u32 v6, v14, 16, 1
	v_add3_u32 v4, v12, v4, s7
	ds_read2_b32 v[24:25], v111 offset0:231 offset1:239
	s_waitcnt lgkmcnt(3)
	v_bfe_u32 v8, v18, 16, 1
	v_add3_u32 v5, v10, v5, s7
	v_add3_u32 v6, v14, v6, s7
	v_lshrrev_b32_e32 v4, 16, v4
	v_add3_u32 v8, v18, v8, s7
	v_lshrrev_b32_e32 v9, 16, v6
	v_and_or_b32 v6, v5, s8, v4
	s_waitcnt lgkmcnt(2)
	v_bfe_u32 v4, v20, 16, 1
	v_lshrrev_b32_e32 v8, 16, v8
	v_add3_u32 v4, v20, v4, s7
	v_and_or_b32 v8, v4, s8, v8
	s_waitcnt lgkmcnt(1)
	v_bfe_u32 v4, v22, 16, 1
	v_bfe_u32 v7, v16, 16, 1
	v_add3_u32 v4, v22, v4, s7
	s_waitcnt lgkmcnt(0)
	v_bfe_u32 v5, v24, 16, 1
	v_add3_u32 v7, v16, v7, s7
	v_lshrrev_b32_e32 v4, 16, v4
	v_add3_u32 v5, v24, v5, s7
	v_and_or_b32 v7, v7, s8, v9
	v_and_or_b32 v9, v5, s8, v4
	v_add_u32_e32 v4, s0, v1
	v_ashrrev_i32_e32 v5, 31, v4
	v_lshlrev_b64 v[26:27], 10, v[4:5]
	v_lshl_add_u64 v[26:27], v[2:3], 0, v[26:27]
	v_bfe_u32 v5, v13, 16, 1
	global_store_dwordx4 v[26:27], v[6:9], off sc1
	v_add3_u32 v5, v13, v5, s7
	v_lshrrev_b32_e32 v5, 16, v5
	v_bfe_u32 v6, v11, 16, 1
	v_add3_u32 v6, v11, v6, s7
	v_and_or_b32 v6, v6, s8, v5
	v_bfe_u32 v5, v15, 16, 1
	v_add3_u32 v5, v15, v5, s7
	v_bfe_u32 v7, v17, 16, 1
	v_lshrrev_b32_e32 v5, 16, v5
	v_add3_u32 v7, v17, v7, s7
	v_and_or_b32 v7, v7, s8, v5
	v_bfe_u32 v5, v19, 16, 1
	v_add3_u32 v5, v19, v5, s7
	v_bfe_u32 v8, v21, 16, 1
	v_lshrrev_b32_e32 v5, 16, v5
	v_add3_u32 v8, v21, v8, s7
	v_and_or_b32 v8, v8, s8, v5
	v_bfe_u32 v5, v23, 16, 1
	v_add_u32_e32 v10, 8, v4
	v_add3_u32 v5, v23, v5, s7
	v_bfe_u32 v9, v25, 16, 1
	v_ashrrev_i32_e32 v11, 31, v10
	v_lshrrev_b32_e32 v5, 16, v5
	v_add3_u32 v9, v25, v9, s7
	v_lshlrev_b64 v[10:11], 10, v[10:11]
	v_and_or_b32 v9, v9, s8, v5
	ds_read2_b32 v[12:13], v111 offset0:16 offset1:24
	v_lshl_add_u64 v[10:11], v[2:3], 0, v[10:11]
	global_store_dwordx4 v[10:11], v[6:9], off sc1
	ds_read2_b32 v[10:11], v111 offset0:49 offset1:57
	ds_read2_b32 v[14:15], v111 offset0:82 offset1:90
	ds_read2_b32 v[16:17], v111 offset0:115 offset1:123
	s_waitcnt lgkmcnt(3)
; #define LAS __attribute__((address_space(3)))
; #define LDS_WAIT() asm volatile("s_waitcnt lgkmcnt(0)" ::: "memory")
; __device__ __forceinline__ unsigned pk2(float lo, float hi) { return f2bf(lo) | (f2bf(hi) << 16); }
; __device__ __forceinline__ void p0_transpose_item(const float* W, int K, int N, bf16* WT, const float* gain, int mode, LAS float* scr, int item, int lane) {
;     const int nblk = N / 64, kb = item / nblk, nb = item % nblk, k0 = 64 * kb, n00 = 64 * nb;
;     f32x4 w[2][8]; float gn[8];
; #pragma unroll
;     for (int hf = 0; hf < 2; ++hf)
; #pragma unroll
;         for (int i = 0; i < 8; ++i) w[hf][i] = __builtin_nontemporal_load((const f32x4*)(W + (size_t)(k0 + (lane >> 3) + 8 * i) * N + n00 + 32 * hf + 4 * (lane & 7)));
; #pragma unroll
;     for (int i = 0; i < 8; ++i) gn[i] = gain ? gain[k0 + (lane >> 3) + 8 * i] : 1.0f;
; #pragma unroll
;     for (int hf = 0; hf < 2; ++hf) { const int n0 = n00 + 32 * hf;
; #pragma unroll
;       for (int i = 0; i < 8; ++i) { const int kk = (lane >> 3) + 8 * i; LAS float* d = scr + kk * 33 + 4 * (lane & 7);
;           d[0] = w[hf][i].x * gn[i]; d[1] = w[hf][i].y * gn[i]; d[2] = w[hf][i].z * gn[i]; d[3] = w[hf][i].w * gn[i]; }
;     LDS_WAIT(); asm volatile("" ::: "memory");
;     const int c = lane & 7;
; #pragma unroll
;     for (int j = 0; j < 4; ++j) { const int n = (lane >> 3) + 8 * j; const LAS float* s = scr + (8 * c) * 33 + n;
;         v4u o; o.x = pk2(s[0 * 33], s[1 * 33]); o.y = pk2(s[2 * 33], s[3 * 33]); o.z = pk2(s[4 * 33], s[5 * 33]); o.w = pk2(s[6 * 33], s[7 * 33]);
;         const int ng = n0 + n; int row;
;         if (mode == 0) row = ng;
;         else if (mode == 3) {
;             if (ng < 512) row = (ng & ~255) + 128 * ((ng >> 5) & 1) + 32 * ((ng >> 6) & 3) + (ng & 31);
;             else if (ng < 640) row = 512 + 128 * ((ng >> 5) & 1) + 32 * ((ng >> 6) & 1) + (ng & 31);
;             else if (ng < 768) { const int vi = ng - 640; row = 512 + 128 * ((vi >> 5) & 1) + 32 * (2 + (vi >> 6)) + (vi & 31); }
;             else row = ng; }
;         else row = (ng >> 7) * 256 + (ng & 127) + (mode == 2 ? 128 : 0);
;         *(v4u*)(WT + (size_t)row * K + k0 + 8 * c) = o; }
;     LDS_WAIT(); asm volatile("" ::: "memory"); }
	v_bfe_u32 v5, v12, 16, 1
	v_add3_u32 v5, v12, v5, s7
	s_waitcnt lgkmcnt(2)
	v_bfe_u32 v6, v10, 16, 1
	ds_read2_b32 v[18:19], v111 offset0:148 offset1:156
	v_lshrrev_b32_e32 v5, 16, v5
	v_add3_u32 v6, v10, v6, s7
	ds_read2_b32 v[20:21], v111 offset0:181 offset1:189
	v_and_or_b32 v6, v6, s8, v5
	s_waitcnt lgkmcnt(3)
	v_bfe_u32 v5, v14, 16, 1
	v_add3_u32 v5, v14, v5, s7
	s_waitcnt lgkmcnt(2)
	v_bfe_u32 v7, v16, 16, 1
	ds_read2_b32 v[22:23], v111 offset0:214 offset1:222
	v_lshrrev_b32_e32 v5, 16, v5
	v_add3_u32 v7, v16, v7, s7
	ds_read2_b32 v[24:25], v111 offset0:247 offset1:255
	v_and_or_b32 v7, v7, s8, v5
	s_waitcnt lgkmcnt(3)
	v_bfe_u32 v5, v18, 16, 1
	v_add3_u32 v5, v18, v5, s7
	s_waitcnt lgkmcnt(2)
	v_bfe_u32 v8, v20, 16, 1
	v_lshrrev_b32_e32 v5, 16, v5
	v_add3_u32 v8, v20, v8, s7
	v_and_or_b32 v8, v8, s8, v5
	s_waitcnt lgkmcnt(1)
	v_bfe_u32 v5, v22, 16, 1
	v_add_u32_e32 v26, 16, v4
	v_add3_u32 v5, v22, v5, s7
	s_waitcnt lgkmcnt(0)
	v_bfe_u32 v9, v24, 16, 1
	v_ashrrev_i32_e32 v27, 31, v26
	v_lshrrev_b32_e32 v5, 16, v5
	v_add3_u32 v9, v24, v9, s7
	v_lshlrev_b64 v[26:27], 10, v[26:27]
	v_and_or_b32 v9, v9, s8, v5
	v_lshl_add_u64 v[26:27], v[2:3], 0, v[26:27]
	v_bfe_u32 v5, v13, 16, 1
	global_store_dwordx4 v[26:27], v[6:9], off sc1
	v_add3_u32 v5, v13, v5, s7
	v_lshrrev_b32_e32 v5, 16, v5
	v_bfe_u32 v6, v11, 16, 1
	v_add3_u32 v6, v11, v6, s7
	v_and_or_b32 v6, v6, s8, v5
	v_bfe_u32 v5, v15, 16, 1
	v_add3_u32 v5, v15, v5, s7
	v_bfe_u32 v7, v17, 16, 1
	v_lshrrev_b32_e32 v5, 16, v5
	v_add3_u32 v7, v17, v7, s7
	v_and_or_b32 v7, v7, s8, v5
	v_bfe_u32 v5, v19, 16, 1
	v_add3_u32 v5, v19, v5, s7
	v_bfe_u32 v8, v21, 16, 1
	v_lshrrev_b32_e32 v5, 16, v5
	v_add3_u32 v8, v21, v8, s7
	v_and_or_b32 v8, v8, s8, v5
	v_bfe_u32 v5, v23, 16, 1
	v_add_u32_e32 v10, 24, v4
	v_add3_u32 v5, v23, v5, s7
	v_bfe_u32 v9, v25, 16, 1
	v_ashrrev_i32_e32 v11, 31, v10
	v_lshrrev_b32_e32 v5, 16, v5
	v_add3_u32 v9, v25, v9, s7
	v_lshlrev_b64 v[10:11], 10, v[10:11]
	v_and_or_b32 v9, v9, s8, v5
	v_lshl_add_u64 v[10:11], v[2:3], 0, v[10:11]
	global_store_dwordx4 v[10:11], v[6:9], off sc1
	s_waitcnt lgkmcnt(0)
	s_waitcnt vmcnt(11)
	ds_write2_b32 v103, v36, v37 offset1:1
	ds_write2_b32 v103, v38, v39 offset0:2 offset1:3
	s_waitcnt vmcnt(10)
	ds_write2_b32 v113, v40, v41 offset1:1
	ds_write2_b32 v113, v42, v43 offset0:2 offset1:3
	s_waitcnt vmcnt(9)
	ds_write2_b32 v115, v44, v45 offset1:1
	ds_write2_b32 v117, v46, v47 offset1:1
	s_waitcnt vmcnt(8)
	ds_write2_b32 v118, v48, v49 offset1:1
	ds_write2_b32 v119, v50, v51 offset1:1
	s_waitcnt vmcnt(7)
	ds_write2_b32 v120, v52, v53 offset1:1
	ds_write2_b32 v121, v54, v55 offset1:1
	s_waitcnt vmcnt(6)
	ds_write2_b32 v122, v56, v57 offset1:1
	ds_write2_b32 v124, v58, v59 offset1:1
	s_waitcnt vmcnt(5)
	ds_write2_b32 v125, v60, v61 offset1:1
	ds_write2_b32 v66, v62, v63 offset1:1
	s_waitcnt vmcnt(4)
	ds_write2_b32 v102, v126, v127 offset1:1
	ds_write2_b32 v104, v128, v129 offset1:1
	s_waitcnt lgkmcnt(0)
	ds_read2_b32 v[10:11], v111 offset1:8
	ds_read2_b32 v[12:13], v111 offset0:33 offset1:41
	ds_read2_b32 v[14:15], v111 offset0:66 offset1:74
	ds_read2_b32 v[16:17], v111 offset0:99 offset1:107
	ds_read2_b32 v[18:19], v111 offset0:132 offset1:140
	s_waitcnt lgkmcnt(4)
	v_bfe_u32 v5, v10, 16, 1
	v_add3_u32 v5, v10, v5, s7
	s_waitcnt lgkmcnt(3)
	v_bfe_u32 v6, v12, 16, 1
	v_lshrrev_b32_e32 v5, 16, v5
	v_add3_u32 v6, v12, v6, s7
	ds_read2_b32 v[20:21], v111 offset0:165 offset1:173
	v_and_or_b32 v6, v6, s8, v5
	s_waitcnt lgkmcnt(3)
	v_bfe_u32 v5, v14, 16, 1
	v_add3_u32 v5, v14, v5, s7
	s_waitcnt lgkmcnt(2)
	v_bfe_u32 v7, v16, 16, 1
	ds_read2_b32 v[22:23], v111 offset0:198 offset1:206
	v_lshrrev_b32_e32 v5, 16, v5
	v_add3_u32 v7, v16, v7, s7
	ds_read2_b32 v[24:25], v111 offset0:231 offset1:239
	v_and_or_b32 v7, v7, s8, v5
	s_waitcnt lgkmcnt(3)
	v_bfe_u32 v5, v18, 16, 1
	v_add3_u32 v5, v18, v5, s7
	s_waitcnt lgkmcnt(2)
; #define LAS __attribute__((address_space(3)))
; #define LDS_WAIT() asm volatile("s_waitcnt lgkmcnt(0)" ::: "memory")
; __device__ __forceinline__ void p0_transpose_item(const float* W, int K, int N, bf16* WT, const float* gain, int mode, LAS float* scr, int item, int lane) {
;     const int nblk = N / 64, kb = item / nblk, nb = item % nblk, k0 = 64 * kb, n00 = 64 * nb;
;     f32x4 w[2][8]; float gn[8];
; #pragma unroll
;     for (int hf = 0; hf < 2; ++hf)
; #pragma unroll
;         for (int i = 0; i < 8; ++i) w[hf][i] = __builtin_nontemporal_load((const f32x4*)(W + (size_t)(k0 + (lane >> 3) + 8 * i) * N + n00 + 32 * hf + 4 * (lane & 7)));
; #pragma unroll
;     for (int i = 0; i < 8; ++i) gn[i] = gain ? gain[k0 + (lane >> 3) + 8 * i] : 1.0f;
; #pragma unroll
;     for (int hf = 0; hf < 2; ++hf) { const int n0 = n00 + 32 * hf;
; #pragma unroll
;       for (int i = 0; i < 8; ++i) { const int kk = (lane >> 3) + 8 * i; LAS float* d = scr + kk * 33 + 4 * (lane & 7);
;           d[0] = w[hf][i].x * gn[i]; d[1] = w[hf][i].y * gn[i]; d[2] = w[hf][i].z * gn[i]; d[3] = w[hf][i].w * gn[i]; }
;     LDS_WAIT(); asm volatile("" ::: "memory");
;     const int c = lane & 7;
; #pragma unroll
;     for (int j = 0; j < 4; ++j) { const int n = (lane >> 3) + 8 * j; const LAS float* s = scr + (8 * c) * 33 + n;
;         v4u o; o.x = pk2(s[0 * 33], s[1 * 33]); o.y = pk2(s[2 * 33], s[3 * 33]); o.z = pk2(s[4 * 33], s[5 * 33]); o.w = pk2(s[6 * 33], s[7 * 33]);
;         const int ng = n0 + n; int row;
;         if (mode == 0) row = ng;
;         else if (mode == 3) {
;             if (ng < 512) row = (ng & ~255) + 128 * ((ng >> 5) & 1) + 32 * ((ng >> 6) & 3) + (ng & 31);
;             else if (ng < 640) row = 512 + 128 * ((ng >> 5) & 1) + 32 * ((ng >> 6) & 1) + (ng & 31);
;             else if (ng < 768) { const int vi = ng - 640; row = 512 + 128 * ((vi >> 5) & 1) + 32 * (2 + (vi >> 6)) + (vi & 31); }
;             else row = ng; }
;         else row = (ng >> 7) * 256 + (ng & 127) + (mode == 2 ? 128 : 0);
;         *(v4u*)(WT + (size_t)row * K + k0 + 8 * c) = o; }
;     LDS_WAIT(); asm volatile("" ::: "memory"); }
; __global__ void __launch_bounds__(NWAVES * 64, 2) mega_fwd(Args args) {
;     ...
;                 if (r < J_GLU) { p0_transpose_item(args.in[18], 512, 512, Wglu, nullptr, 0, scr, r, lane); continue; } r -= J_GLU;
	v_bfe_u32 v8, v20, 16, 1
	v_lshrrev_b32_e32 v5, 16, v5
	v_add3_u32 v8, v20, v8, s7
	v_and_or_b32 v8, v8, s8, v5
	s_waitcnt lgkmcnt(1)
	v_bfe_u32 v5, v22, 16, 1
	v_add_u32_e32 v26, 32, v4
	v_add3_u32 v5, v22, v5, s7
	s_waitcnt lgkmcnt(0)
	v_bfe_u32 v9, v24, 16, 1
	v_ashrrev_i32_e32 v27, 31, v26
	v_lshrrev_b32_e32 v5, 16, v5
	v_add3_u32 v9, v24, v9, s7
	v_lshlrev_b64 v[26:27], 10, v[26:27]
	v_and_or_b32 v9, v9, s8, v5
	v_lshl_add_u64 v[26:27], v[2:3], 0, v[26:27]
	v_bfe_u32 v5, v11, 16, 1
	global_store_dwordx4 v[26:27], v[6:9], off sc1
	v_add3_u32 v5, v11, v5, s7
	v_lshrrev_b32_e32 v5, 16, v5
	v_bfe_u32 v6, v13, 16, 1
	v_add3_u32 v6, v13, v6, s7
	v_and_or_b32 v6, v6, s8, v5
	v_bfe_u32 v5, v15, 16, 1
	v_add3_u32 v5, v15, v5, s7
	v_bfe_u32 v7, v17, 16, 1
	v_lshrrev_b32_e32 v5, 16, v5
	v_add3_u32 v7, v17, v7, s7
	v_and_or_b32 v7, v7, s8, v5
	v_bfe_u32 v5, v19, 16, 1
	v_add3_u32 v5, v19, v5, s7
	v_bfe_u32 v8, v21, 16, 1
	v_lshrrev_b32_e32 v5, 16, v5
	v_add3_u32 v8, v21, v8, s7
	v_and_or_b32 v8, v8, s8, v5
	v_bfe_u32 v5, v23, 16, 1
	v_add_u32_e32 v10, 40, v4
	v_add3_u32 v5, v23, v5, s7
	v_bfe_u32 v9, v25, 16, 1
	v_ashrrev_i32_e32 v11, 31, v10
	v_lshrrev_b32_e32 v5, 16, v5
	v_add3_u32 v9, v25, v9, s7
	v_lshlrev_b64 v[10:11], 10, v[10:11]
	v_and_or_b32 v9, v9, s8, v5
	ds_read2_b32 v[12:13], v111 offset0:16 offset1:24
	v_lshl_add_u64 v[10:11], v[2:3], 0, v[10:11]
	global_store_dwordx4 v[10:11], v[6:9], off sc1
	ds_read2_b32 v[10:11], v111 offset0:49 offset1:57
	ds_read2_b32 v[14:15], v111 offset0:82 offset1:90
	ds_read2_b32 v[16:17], v111 offset0:115 offset1:123
	s_waitcnt lgkmcnt(3)
	v_bfe_u32 v5, v12, 16, 1
	v_add3_u32 v5, v12, v5, s7
	s_waitcnt lgkmcnt(2)
	v_bfe_u32 v6, v10, 16, 1
	ds_read2_b32 v[18:19], v111 offset0:148 offset1:156
	v_lshrrev_b32_e32 v5, 16, v5
	v_add3_u32 v6, v10, v6, s7
	ds_read2_b32 v[20:21], v111 offset0:181 offset1:189
	v_and_or_b32 v6, v6, s8, v5
	s_waitcnt lgkmcnt(3)
	v_bfe_u32 v5, v14, 16, 1
	v_add3_u32 v5, v14, v5, s7
	s_waitcnt lgkmcnt(2)
	v_bfe_u32 v7, v16, 16, 1
	ds_read2_b32 v[22:23], v111 offset0:214 offset1:222
	v_lshrrev_b32_e32 v5, 16, v5
	v_add3_u32 v7, v16, v7, s7
	ds_read2_b32 v[24:25], v111 offset0:247 offset1:255
	v_and_or_b32 v7, v7, s8, v5
	s_waitcnt lgkmcnt(3)
	v_bfe_u32 v5, v18, 16, 1
	v_add3_u32 v5, v18, v5, s7
	s_waitcnt lgkmcnt(2)
	v_bfe_u32 v8, v20, 16, 1
	v_lshrrev_b32_e32 v5, 16, v5
	v_add3_u32 v8, v20, v8, s7
	v_and_or_b32 v8, v8, s8, v5
	s_waitcnt lgkmcnt(1)
	v_bfe_u32 v5, v22, 16, 1
	v_add_u32_e32 v26, 48, v4
	v_add3_u32 v5, v22, v5, s7
	s_waitcnt lgkmcnt(0)
	v_bfe_u32 v9, v24, 16, 1
	v_ashrrev_i32_e32 v27, 31, v26
	v_lshrrev_b32_e32 v5, 16, v5
	v_add3_u32 v9, v24, v9, s7
	v_lshlrev_b64 v[26:27], 10, v[26:27]
	v_and_or_b32 v9, v9, s8, v5
	v_lshl_add_u64 v[26:27], v[2:3], 0, v[26:27]
	v_bfe_u32 v5, v13, 16, 1
	global_store_dwordx4 v[26:27], v[6:9], off sc1
	v_add3_u32 v5, v13, v5, s7
	v_lshrrev_b32_e32 v5, 16, v5
	v_add_u32_e32 v8, 56, v4
	v_bfe_u32 v4, v11, 16, 1
	v_add3_u32 v4, v11, v4, s7
	v_bfe_u32 v6, v15, 16, 1
	v_and_or_b32 v4, v4, s8, v5
	v_bfe_u32 v5, v17, 16, 1
	v_add3_u32 v6, v15, v6, s7
	v_add3_u32 v5, v17, v5, s7
	v_lshrrev_b32_e32 v6, 16, v6
	v_bfe_u32 v7, v19, 16, 1
	v_and_or_b32 v5, v5, s8, v6
	v_bfe_u32 v6, v21, 16, 1
	v_add3_u32 v7, v19, v7, s7
	v_add3_u32 v6, v21, v6, s7
	v_lshrrev_b32_e32 v7, 16, v7
	v_bfe_u32 v9, v23, 16, 1
	v_and_or_b32 v6, v6, s8, v7
	v_bfe_u32 v7, v25, 16, 1
	v_add3_u32 v9, v23, v9, s7
	v_add3_u32 v7, v25, v7, s7
	v_lshrrev_b32_e32 v9, 16, v9
	v_and_or_b32 v7, v7, s8, v9
	v_ashrrev_i32_e32 v9, 31, v8
	v_lshlrev_b64 v[8:9], 10, v[8:9]
	v_lshl_add_u64 v[2:3], v[2:3], 0, v[8:9]
	global_store_dwordx4 v[2:3], v[4:7], off sc1
	s_waitcnt lgkmcnt(0)
	s_waitcnt vmcnt(0)
	s_mov_b64 s[0:1], exec
	s_mov_b64 exec, 1
	v_readlane_b32 s16, v252, 26
	v_readlane_b32 s17, v252, 27
	v_mov_b32_e32 v200, 0x4000
	v_mov_b32_e32 v201, 1
	s_nop 4
	global_atomic_add v200, v201, s[16:17]
	s_mov_b64 exec, s[0:1]
	s_branch .LBB0_835
